# v3 + attention work queue split per XCD (units sharing K/V on one L2)
# baseline (speedup 1.0000x reference)
.LBB0_151:
	v_readlane_b32 s0, v252, 0
	s_mov_b32 s78, s0
	v_readlane_b32 s0, v254, 5
	s_ashr_i32 s2, s0, 2
	s_and_b32 s3, s0, 3
	s_lshl_b32 s0, s2, 6
	s_ashr_i32 s1, s0, 31
	v_writelane_b32 v254, s0, 8
	s_lshl_b32 s79, s2, 5
	s_lshl_b32 s4, s2, 9
	v_writelane_b32 v254, s1, 9
	s_mov_b32 s0, s2
	v_writelane_b32 v254, s0, 10
	s_mov_b64 s[10:11], -1
	s_mov_b64 s[12:13], 0
	v_writelane_b32 v254, s1, 11
	s_lshl_b32 s0, s2, 4
	v_writelane_b32 v254, s0, 12
	v_writelane_b32 v254, s73, 13
	v_writelane_b32 v254, s80, 14
	s_cmp_lt_i32 s3, 2
	s_mov_b64 s[8:9], 0
	v_writelane_b32 v254, s81, 15
	s_cbranch_scc1 .LBB0_359
	s_cmp_eq_u32 s3, 2
	s_mov_b64 s[8:9], -1
	s_cbranch_scc0 .LBB0_358
	v_writelane_b32 v254, s3, 16
	v_cmp_eq_u32_e64 s[42:43], 0, v218
	v_readlane_b32 s0, v254, 8
	v_readlane_b32 s1, v254, 9
	s_lshl_b64 s[2:3], s[0:1], 2
	v_readlane_b32 s0, v252, 13
	s_add_u32 s2, s0, s2
	v_readlane_b32 s0, v252, 14
	s_addc_u32 s3, s0, s3
	v_writelane_b32 v254, s2, 17
	s_nop 1
	v_writelane_b32 v254, s3, 18
	s_nop 0
	v_readlane_b32 s0, v254, 10
	v_readlane_b32 s1, v254, 11
	s_lshl_b32 s0, s0, 3
	s_ashr_i32 s1, s0, 31
	v_writelane_b32 v254, s0, 19
	s_nop 1
	v_writelane_b32 v254, s1, 20
	s_add_u32 s0, s88, 0x4800000
	v_writelane_b32 v254, s0, 21
	s_addc_u32 s0, s89, 0
	v_writelane_b32 v254, s0, 23
	s_add_u32 s0, s88, 0x4e00000
	v_writelane_b32 v254, s0, 24
	s_addc_u32 s0, s89, 0
	v_writelane_b32 v254, s0, 25
	s_add_u32 s0, s88, 0x5000000
	v_writelane_b32 v254, s0, 26
	s_addc_u32 s0, s89, 0
	v_writelane_b32 v254, s0, 27
	s_add_u32 s0, s88, 0x6900000
	v_writelane_b32 v254, s0, 28
	s_addc_u32 s0, s89, 0
	v_writelane_b32 v254, s0, 30
	s_add_u32 s0, s88, 0x8200000
	v_writelane_b32 v254, s0, 31
	s_addc_u32 s0, s89, 0
	v_writelane_b32 v254, s0, 33
	s_add_u32 s0, s88, 0x8e00000
	v_writelane_b32 v254, s0, 34
	s_addc_u32 s0, s89, 0
	v_writelane_b32 v254, s0, 36
	s_add_u32 s0, s88, 0x5800000
	v_writelane_b32 v254, s0, 37
	s_addc_u32 s0, s89, 0
	v_writelane_b32 v254, s0, 39
	s_add_u32 s0, s88, 0xa00000
	v_writelane_b32 v254, s0, 41
	s_addc_u32 s0, s89, 0
	v_writelane_b32 v254, s0, 43
	s_add_u32 s0, s88, 0x400000
	v_writelane_b32 v254, s0, 44
	s_addc_u32 s0, s89, 0
	v_writelane_b32 v254, s0, 46
	s_add_u32 s0, s88, 0x600000
	v_writelane_b32 v254, s0, 48
	s_addc_u32 s0, s89, 0
	v_writelane_b32 v254, s0, 50
	s_add_u32 s0, s88, 0x3c00000
	v_writelane_b32 v254, s0, 52
	s_addc_u32 s0, s89, 0
	v_writelane_b32 v254, s0, 53
	s_add_u32 s0, s88, 0x4000000
	v_writelane_b32 v254, s0, 54
	s_addc_u32 s0, s89, 0
	v_writelane_b32 v254, s0, 56
	s_add_u32 s0, s88, 0x4400000
	v_writelane_b32 v254, s0, 57
	s_addc_u32 s0, s89, 0
	s_cmp_eq_u32 s73, 0
	v_writelane_b32 v254, s0, 58
	s_cselect_b64 s[12:13], -1, 0
	s_add_u32 s0, s88, 0x8000
	v_writelane_b32 v254, s0, 59
	s_addc_u32 s0, s89, 0
	s_add_u32 s14, s88, 0x4200
	v_writelane_b32 v254, s0, 60
	s_addc_u32 s15, s89, 0
	s_and_b32 s0, s73, 3
	s_ashr_i32 s2, s73, 2
	s_lshl_b32 s1, s2, 5
	s_lshl_b32 s2, s2, 12
	s_lshl_b32 s3, s0, 10
	s_or_b32 s80, s2, s3
	s_lshl_b32 s51, s73, 5
	s_lshl_b32 s5, s0, 12
	s_addk_i32 s80, 0x3000
	s_lshl_b32 s16, s73, 10
	s_lshl_b32 s10, s73, 3
	s_and_b32 s6, s51, 32
	s_add_i32 s7, s5, s1
	s_add_i32 s17, s16, 0
	s_add_i32 s38, s80, 0
	s_bfe_u32 s2, s73, 0x10001
	s_cmp_eq_u32 s2, 0
	s_cselect_b64 s[8:9], -1, 0
	v_writelane_b32 v254, s8, 61
	s_add_u32 s5, s88, 0xa200
	s_mov_b32 s81, s1
	v_writelane_b32 v254, s9, 62
	v_writelane_b32 v254, s5, 63
	s_addc_u32 s5, s89, 0
	s_cmp_lt_i32 s73, 4
	v_writelane_b32 v255, s5, 0
	s_cselect_b64 s[8:9], -1, 0
	v_writelane_b32 v255, s8, 2
	s_lshl_b32 s2, s2, 16
	v_readlane_b32 s5, v252, 15
	v_writelane_b32 v255, s9, 3
	s_add_u32 s2, s5, s2
	v_readlane_b32 s5, v252, 16
	s_addc_u32 s5, s5, 0
	v_writelane_b32 v255, s6, 4
	s_lshl_b32 s6, s6, 8
	s_add_u32 s2, s2, s6
	v_writelane_b32 v255, s2, 6
	s_addc_u32 s2, s5, 0
	v_writelane_b32 v255, s2, 7
	s_add_u32 s2, s88, 0x300000
	v_writelane_b32 v255, s2, 8
	s_addc_u32 s2, s89, 0
	s_add_u32 s39, s88, 0x1800
	s_addc_u32 s8, s89, 0
	v_writelane_b32 v255, s2, 9
	s_add_u32 s2, s88, 0x9000
	v_writelane_b32 v255, s2, 10
	s_addc_u32 s2, s89, 0
	v_writelane_b32 v255, s2, 11
	s_lshl_b32 s2, s73, 9
	s_add_i32 s2, s2, 0
	s_add_i32 s2, s2, 0x21800
	v_writelane_b32 v255, s2, 12
	s_add_u32 s18, s88, 0x5900000
	s_mul_i32 s2, s73, 0x2200
	s_addc_u32 s19, s89, 0
	s_add_i32 s9, s2, 0
	s_add_u32 s26, s88, 0x7200000
	s_addc_u32 s27, s89, 0
	s_lshl_b32 s2, s0, 11
	v_writelane_b32 v255, s7, 13
	s_sub_i32 s5, s7, s2
	v_writelane_b32 v255, s5, 14
	s_lshl_b32 s5, s73, 7
	s_add_i32 s6, s5, 0
	s_add_i32 s6, s6, 0x22800
	s_add_u32 s5, s88, 0x9800
	v_writelane_b32 v255, s5, 15
	s_addc_u32 s5, s89, 0
	v_writelane_b32 v255, s5, 16
	s_add_u32 s5, s88, 0x8800
	v_writelane_b32 v255, s5, 17
	s_addc_u32 s5, s89, 0
	v_writelane_b32 v255, s5, 18
	s_lshl_b32 s5, s0, 4
	s_add_i32 s3, s3, 0
	v_writelane_b32 v255, s5, 19
	s_add_i32 s7, s3, 0x2000
	v_writelane_b32 v255, s3, 20
	s_add_u32 s3, s88, 0x4410000
	v_writelane_b32 v255, s3, 22
	s_addc_u32 s3, s89, 0
	v_writelane_b32 v255, s3, 23
	s_add_u32 s3, s88, 0x4010000
	v_writelane_b32 v255, s3, 24
	s_addc_u32 s3, s89, 0
	v_writelane_b32 v255, s3, 25
	s_lshl_b32 s3, s73, 11
	v_writelane_b32 v255, s3, 26
	s_add_i32 s2, s2, s1
	v_writelane_b32 v255, s2, 27
	s_lshl_b32 s2, s0, 9
	s_mulk_i32 s0, 0x3000
	v_writelane_b32 v255, s2, 29
	s_add_i32 s0, s0, s1
	v_writelane_b32 v255, s0, 30
	s_getreg_b32 s100, hwreg(HW_REG_XCC_ID, 0, 4)
	s_and_b32 s100, s100, 7
	s_branch .LBB0_156

.LBB0_156:
	s_waitcnt lgkmcnt(0)
	s_barrier
	s_and_saveexec_b64 s[28:29], s[42:43]
	s_cbranch_execz .LBB0_160
	s_mov_b64 s[40:41], exec
	v_mbcnt_lo_u32_b32 v0, s40, 0
	v_mbcnt_hi_u32_b32 v0, s41, v0
	v_cmp_eq_u32_e32 vcc, 0, v0
	s_and_saveexec_b64 s[34:35], vcc
	s_cbranch_execz .LBB0_159
	s_bcnt1_i32_b64 s0, s[40:41]
	v_mov_b32_e32 v1, s0
	v_mov_b32_e32 v2, s100
	v_lshlrev_b32_e32 v2, 4, v2
	v_readlane_b32 s0, v254, 17
	v_readlane_b32 s1, v254, 18
	s_nop 4
	global_atomic_add v1, v2, v1, s[0:1] sc0

.LBB0_160:
	s_or_b64 exec, exec, s[28:29]
	v_readlane_b32 s0, v253, 61
	s_waitcnt lgkmcnt(0)
	s_barrier
	v_mov_b32_e32 v0, s0
	ds_read_b32 v0, v0
	s_mov_b64 s[28:29], -1
	s_waitcnt lgkmcnt(0)
	v_readfirstlane_b32 s0, v0
	s_cmpk_gt_i32 s0, 0x47
	s_cbranch_scc1 .LBB0_155
	s_mul_i32 s2, s100, 12
	s_lshl_b32 s3, s100, 3
	s_cmpk_lt_i32 s0, 12
	s_cbranch_scc1 .Lqm_gqa
	s_cmpk_lt_i32 s0, 20
	s_cbranch_scc1 .Lqm_ret
	s_cmpk_lt_i32 s0, 32
	s_cbranch_scc1 .Lqm_mla
	s_cmpk_lt_i32 s0, 44
	s_cbranch_scc1 .Lqm_cgqa
	s_cmpk_lt_i32 s0, 52
	s_cbranch_scc1 .Lqm_cret
	s_cmpk_lt_i32 s0, 64
	s_cbranch_scc1 .Lqm_cmla
	s_add_i32 s5, s0, 0x1c0
	s_add_i32 s5, s5, s3
	s_branch .LBB0_173
.Lqm_gqa:
	s_add_i32 s5, s0, 0x60
	s_add_i32 s5, s5, s2
	s_branch .LBB0_173
.Lqm_ret:
	s_add_i32 s5, s0, 0xb4
	s_add_i32 s5, s5, s3
	s_branch .LBB0_173
.Lqm_mla:
	s_add_i32 s5, s0, 0xffffffec
	s_add_i32 s5, s5, s2
	s_branch .LBB0_173
.Lqm_cgqa:
	s_add_i32 s5, s0, 0x140
	s_add_i32 s5, s5, s2
	s_branch .LBB0_173
.Lqm_cret:
	s_add_i32 s5, s0, 0x194
	s_add_i32 s5, s5, s3
	s_branch .LBB0_173
.Lqm_cmla:
	s_add_i32 s5, s0, 0xcc
	s_add_i32 s5, s5, s2
